# all three GEMM K-loops: LDS-DMA loads with scalar base use SGPR-base + 32-bit VGPR offset form; dead 64-bit VALU address adds removed
# baseline (speedup 1.0000x reference)
; #define PG8_STAGE(bufoff, gbase, voff) do { _Pragma("unroll") for (int _i = 0; _i < 2; ++_i) \
;         __builtin_amdgcn_global_load_lds((const unsigned*)((const char*)(gbase) + (voff)[_i]), (LAS unsigned*)(lds + (bufoff) + ldsw + _i * 8192), 16, 0, 0); } while (0)
; #define PG8_LDA(dst, b, h) do { _Pragma("unroll") for (int m = 0; m < 4; ++m) _Pragma("unroll") for (int k = 0; k < 2; ++k) dst[m][k] = *(const LAS bf16x8*)(lds + PG8_SA(b, h) + aoff + m * 2048 + k * 1024); } while (0)
; #define PG8_LDB(dst, b, h) do { _Pragma("unroll") for (int n = 0; n < 2; ++n) _Pragma("unroll") for (int k = 0; k < 2; ++k) dst[n][k] = *(const LAS bf16x8*)(lds + PG8_SB(b, h) + boff + n * 2048 + k * 1024); } while (0)
; #define PG8_SCHED __builtin_amdgcn_sched_barrier(0)
; template <class Epi>
; DI void gemm_phase(LAS unsigned char* lds, const int tid, const Gemm g, const StaticOrder& S, const Epi& E) {
;     ...
;         for (int t = 0; t < nt; t += 2) {
;             const bool last = (t == nt - 2);
;             const char* a1 = cA + (size_t)(t + 1) * kstep;
;             const char* a2 = last ? nA : cA + (size_t)(t + 2) * kstep; const char* b2 = last ? nB : cB + (size_t)(t + 2) * kstep;
;             const char* a3 = a2 + kstep; const char* b3 = b2 + kstep;
;             PG8_LDB(B0, 0, 0); PG8_LDB(B1, 0, 1); PG8_SCHED; PG8_LDA(At, 0, 0); PG8_STAGE(PG8_SA(1, 1), a1 + hstepA, voffA);
.Lin_rs_skip:
	s_add_u32 s26, s58, 0xfffc0080
	s_addc_u32 s27, s59, -1
	s_add_i32 s83, 0, 0x10000
	s_cmp_eq_u32 s82, 12
	s_cselect_b32 s63, s49, s27
	s_cselect_b32 s62, s78, s26
	v_add_u32_e32 v144, s83, v147
	s_cselect_b32 s61, s37, s81
	s_cselect_b32 s60, s79, s80
	s_add_i32 s84, 0, 0x14000
	ds_read_b128 v[140:143], v144
	ds_read_b128 v[152:155], v144 offset:1024
	ds_read_b128 v[156:159], v144 offset:2048
	ds_read_b128 v[160:163], v144 offset:3072
	v_add_u32_e32 v144, s84, v147
	ds_read_b128 v[164:167], v144
	ds_read_b128 v[168:171], v144 offset:1024
	ds_read_b128 v[172:175], v144 offset:2048
	ds_read_b128 v[176:179], v144 offset:3072
	s_add_i32 m0, s42, 0xc000
	ds_read_b128 v[180:183], v150
	ds_read_b128 v[184:187], v150 offset:1024
	ds_read_b128 v[188:191], v150 offset:2048
	ds_read_b128 v[192:195], v150 offset:3072
	ds_read_b128 v[196:199], v150 offset:4096
	ds_read_b128 v[200:203], v150 offset:5120
	ds_read_b128 v[208:211], v150 offset:6144
	ds_read_b128 v[212:215], v150 offset:7168
	global_load_lds_dwordx4 v136, s[58:59]
	s_add_i32 m0, s42, 0xe000
	s_nop 0
	global_load_lds_dwordx4 v138, s[58:59]
	s_cmp_eq_u32 s100, 0
	s_cbranch_scc1 .Lin_ws1
	s_cmp_eq_u32 s100, 1
	s_cbranch_scc1 .Lin_wr1
	s_waitcnt vmcnt(24)
	s_branch .Lin_wq1

; #define PG8_STAGE(bufoff, gbase, voff) do { _Pragma("unroll") for (int _i = 0; _i < 2; ++_i) \
;         __builtin_amdgcn_global_load_lds((const unsigned*)((const char*)(gbase) + (voff)[_i]), (LAS unsigned*)(lds + (bufoff) + ldsw + _i * 8192), 16, 0, 0); } while (0)
; #define PG8_LDA(dst, b, h) do { _Pragma("unroll") for (int m = 0; m < 4; ++m) _Pragma("unroll") for (int k = 0; k < 2; ++k) dst[m][k] = *(const LAS bf16x8*)(lds + PG8_SA(b, h) + aoff + m * 2048 + k * 1024); } while (0)
; #define PG8_MMA(ai, bj, At, Bt) do { __builtin_amdgcn_s_setprio(1); _Pragma("unroll") for (int m = 0; m < 4; ++m) _Pragma("unroll") for (int n = 0; n < 2; ++n) _Pragma("unroll") for (int k = 0; k < 2; ++k) \
;         acc[ai][bj][m][n] = __builtin_amdgcn_mfma_f32_16x16x32_bf16(Bt[n][k], At[m][k], acc[ai][bj][m][n], 0, 0, 0); __builtin_amdgcn_s_setprio(0); } while (0)
; #define PG8_WAIT_V(n) asm volatile("s_waitcnt vmcnt(" #n ")" ::: "memory")
; #define PG8_WAIT_L(n) asm volatile("s_waitcnt lgkmcnt(" #n ")" ::: "memory")
; #define PG8_BAR __builtin_amdgcn_s_barrier()
; #define PG8_SCHED __builtin_amdgcn_sched_barrier(0)
; template <class Epi>
; DI void gemm_phase(LAS unsigned char* lds, const int tid, const Gemm g, const StaticOrder& S, const Epi& E) {
;     ...
;             PG8_WAIT_V(8); PG8_WAIT_L(0); PG8_BAR; PG8_MMA(0, 0, At, B0); PG8_MMA(0, 1, At, B1); PG8_BAR; PG8_SCHED;
;             PG8_LDA(At, 0, 1); PG8_STAGE(PG8_SB(0, 0), b2, voffB); PG8_STAGE(PG8_SB(0, 1), b2 + hstepB, voffB); PG8_STAGE(PG8_SA(0, 0), a2, voffA);
.Lin_wd1:
	s_waitcnt lgkmcnt(0)
	s_barrier
	s_setprio 1
	s_waitcnt lgkmcnt(0)
	v_mfma_f32_16x16x32_bf16 v[126:129], v[140:143], v[180:183], v[126:129]
	v_mfma_f32_16x16x32_bf16 v[122:125], v[156:159], v[180:183], v[122:125]
	v_mfma_f32_16x16x32_bf16 v[118:121], v[140:143], v[188:191], v[118:121]
	v_mfma_f32_16x16x32_bf16 v[110:113], v[156:159], v[188:191], v[110:113]
	v_mfma_f32_16x16x32_bf16 v[102:105], v[140:143], v[196:199], v[102:105]
	v_mfma_f32_16x16x32_bf16 v[94:97], v[156:159], v[196:199], v[94:97]
	v_mfma_f32_16x16x32_bf16 v[86:89], v[140:143], v[208:211], v[86:89]
	v_mfma_f32_16x16x32_bf16 v[78:81], v[156:159], v[208:211], v[78:81]
	v_mfma_f32_16x16x32_bf16 v[126:129], v[152:155], v[184:187], v[126:129]
	v_mfma_f32_16x16x32_bf16 v[122:125], v[160:163], v[184:187], v[122:125]
	v_mfma_f32_16x16x32_bf16 v[118:121], v[152:155], v[192:195], v[118:121]
	v_mfma_f32_16x16x32_bf16 v[110:113], v[160:163], v[192:195], v[110:113]
	v_mfma_f32_16x16x32_bf16 v[102:105], v[152:155], v[200:203], v[102:105]
	v_mfma_f32_16x16x32_bf16 v[94:97], v[160:163], v[200:203], v[94:97]
	v_mfma_f32_16x16x32_bf16 v[86:89], v[152:155], v[212:215], v[86:89]
	v_mfma_f32_16x16x32_bf16 v[78:81], v[160:163], v[212:215], v[78:81]
	s_setprio 0
	s_setprio 1
	v_mfma_f32_16x16x32_bf16 v[114:117], v[164:167], v[180:183], v[114:117]
	v_mfma_f32_16x16x32_bf16 v[106:109], v[172:175], v[180:183], v[106:109]
	v_mfma_f32_16x16x32_bf16 v[98:101], v[164:167], v[188:191], v[98:101]
	v_mfma_f32_16x16x32_bf16 v[90:93], v[172:175], v[188:191], v[90:93]
	v_mfma_f32_16x16x32_bf16 v[82:85], v[164:167], v[196:199], v[82:85]
	v_mfma_f32_16x16x32_bf16 v[74:77], v[172:175], v[196:199], v[74:77]
	v_mfma_f32_16x16x32_bf16 v[70:73], v[164:167], v[208:211], v[70:73]
	v_mfma_f32_16x16x32_bf16 v[66:69], v[172:175], v[208:211], v[66:69]
	v_mfma_f32_16x16x32_bf16 v[114:117], v[168:171], v[184:187], v[114:117]
	v_mfma_f32_16x16x32_bf16 v[106:109], v[176:179], v[184:187], v[106:109]
	v_mfma_f32_16x16x32_bf16 v[98:101], v[168:171], v[192:195], v[98:101]
	v_mfma_f32_16x16x32_bf16 v[90:93], v[176:179], v[192:195], v[90:93]
	v_mfma_f32_16x16x32_bf16 v[82:85], v[168:171], v[200:203], v[82:85]
	v_mfma_f32_16x16x32_bf16 v[74:77], v[176:179], v[200:203], v[74:77]
	v_mfma_f32_16x16x32_bf16 v[70:73], v[168:171], v[212:215], v[70:73]
	v_mfma_f32_16x16x32_bf16 v[66:69], v[176:179], v[212:215], v[66:69]
	s_setprio 0
	s_barrier
	s_add_i32 s26, s83, s30
	v_lshl_add_u64 v[204:205], s[60:61], 0, v[0:1]
	s_mov_b32 m0, s26
	ds_read_b128 v[180:183], v150 offset:16384
	ds_read_b128 v[184:187], v150 offset:17408
	ds_read_b128 v[188:191], v150 offset:18432
	ds_read_b128 v[192:195], v150 offset:19456
	ds_read_b128 v[196:199], v150 offset:20480
	ds_read_b128 v[200:203], v150 offset:21504
	ds_read_b128 v[208:211], v150 offset:22528
	ds_read_b128 v[212:215], v150 offset:23552
	global_load_lds_dwordx4 v0, s[60:61]
	s_add_i32 m0, s26, 0x2000
	s_add_u32 s26, s60, 0x40000
	v_lshl_add_u64 v[216:217], s[60:61], 0, v[130:131]
	s_addc_u32 s27, s61, 0
	s_add_i32 s83, s84, s30
	global_load_lds_dwordx4 v130, s[60:61]
	s_mov_b32 m0, s83
	v_lshl_add_u64 v[220:221], s[62:63], 0, v[132:133]
	global_load_lds_dwordx4 v0, s[26:27]
	s_add_i32 m0, s83, 0x2000
	s_nop 0
	global_load_lds_dwordx4 v130, s[26:27]
	v_lshl_add_u64 v[218:219], s[62:63], 0, v[134:135]
	s_mov_b32 m0, s42
	s_nop 0
	global_load_lds_dwordx4 v134, s[62:63]
	s_mov_b32 m0, s43
	s_nop 0
	global_load_lds_dwordx4 v132, s[62:63]
	s_cmp_eq_u32 s100, 0
	s_cbranch_scc1 .Lin_ws2
	s_cmp_eq_u32 s100, 1
	s_cbranch_scc1 .Lin_wr2
	s_waitcnt vmcnt(24)
	s_branch .Lin_wq2

; #define PG8_STAGE(bufoff, gbase, voff) do { _Pragma("unroll") for (int _i = 0; _i < 2; ++_i) \
;         __builtin_amdgcn_global_load_lds((const unsigned*)((const char*)(gbase) + (voff)[_i]), (LAS unsigned*)(lds + (bufoff) + ldsw + _i * 8192), 16, 0, 0); } while (0)
; #define PG8_LDA(dst, b, h) do { _Pragma("unroll") for (int m = 0; m < 4; ++m) _Pragma("unroll") for (int k = 0; k < 2; ++k) dst[m][k] = *(const LAS bf16x8*)(lds + PG8_SA(b, h) + aoff + m * 2048 + k * 1024); } while (0)
; #define PG8_LDB(dst, b, h) do { _Pragma("unroll") for (int n = 0; n < 2; ++n) _Pragma("unroll") for (int k = 0; k < 2; ++k) dst[n][k] = *(const LAS bf16x8*)(lds + PG8_SB(b, h) + boff + n * 2048 + k * 1024); } while (0)
; #define PG8_MMA(ai, bj, At, Bt) do { __builtin_amdgcn_s_setprio(1); _Pragma("unroll") for (int m = 0; m < 4; ++m) _Pragma("unroll") for (int n = 0; n < 2; ++n) _Pragma("unroll") for (int k = 0; k < 2; ++k) \
;         acc[ai][bj][m][n] = __builtin_amdgcn_mfma_f32_16x16x32_bf16(Bt[n][k], At[m][k], acc[ai][bj][m][n], 0, 0, 0); __builtin_amdgcn_s_setprio(0); } while (0)
; #define PG8_WAIT_V(n) asm volatile("s_waitcnt vmcnt(" #n ")" ::: "memory")
; #define PG8_WAIT_L(n) asm volatile("s_waitcnt lgkmcnt(" #n ")" ::: "memory")
; #define PG8_BAR __builtin_amdgcn_s_barrier()
; #define PG8_SCHED __builtin_amdgcn_sched_barrier(0)
; template <class Epi>
; DI void gemm_phase(LAS unsigned char* lds, const int tid, const Gemm g, const StaticOrder& S, const Epi& E) {
;     ...
;             PG8_WAIT_V(8); PG8_WAIT_L(0); PG8_BAR; PG8_MMA(1, 0, At, B0); PG8_MMA(1, 1, At, B1); PG8_BAR; PG8_SCHED;
;             PG8_LDB(B0, 1, 0); PG8_LDB(B1, 1, 1); PG8_SCHED; PG8_LDA(At, 1, 0); PG8_STAGE(PG8_SA(0, 1), a2 + hstepA, voffA);
;             PG8_WAIT_V(8); PG8_WAIT_L(0); PG8_BAR; PG8_MMA(0, 0, At, B0); PG8_MMA(0, 1, At, B1); PG8_BAR; PG8_SCHED;
.Lin_wd2:
	s_waitcnt lgkmcnt(0)
	s_barrier
	s_setprio 1
	s_waitcnt lgkmcnt(0)
	v_mfma_f32_16x16x32_bf16 v[62:65], v[140:143], v[180:183], v[62:65]
	v_mfma_f32_16x16x32_bf16 v[58:61], v[156:159], v[180:183], v[58:61]
	v_mfma_f32_16x16x32_bf16 v[54:57], v[140:143], v[188:191], v[54:57]
	v_mfma_f32_16x16x32_bf16 v[46:49], v[156:159], v[188:191], v[46:49]
	v_mfma_f32_16x16x32_bf16 v[38:41], v[140:143], v[196:199], v[38:41]
	v_mfma_f32_16x16x32_bf16 v[30:33], v[156:159], v[196:199], v[30:33]
	v_mfma_f32_16x16x32_bf16 v[22:25], v[140:143], v[208:211], v[22:25]
	v_mfma_f32_16x16x32_bf16 v[14:17], v[156:159], v[208:211], v[14:17]
	v_mfma_f32_16x16x32_bf16 v[62:65], v[152:155], v[184:187], v[62:65]
	v_mfma_f32_16x16x32_bf16 v[58:61], v[160:163], v[184:187], v[58:61]
	v_mfma_f32_16x16x32_bf16 v[54:57], v[152:155], v[192:195], v[54:57]
	v_mfma_f32_16x16x32_bf16 v[46:49], v[160:163], v[192:195], v[46:49]
	v_mfma_f32_16x16x32_bf16 v[38:41], v[152:155], v[200:203], v[38:41]
	v_mfma_f32_16x16x32_bf16 v[30:33], v[160:163], v[200:203], v[30:33]
	v_mfma_f32_16x16x32_bf16 v[22:25], v[152:155], v[212:215], v[22:25]
	v_mfma_f32_16x16x32_bf16 v[14:17], v[160:163], v[212:215], v[14:17]
	s_setprio 0
	s_setprio 1
	v_mfma_f32_16x16x32_bf16 v[50:53], v[164:167], v[180:183], v[50:53]
	v_mfma_f32_16x16x32_bf16 v[42:45], v[172:175], v[180:183], v[42:45]
	v_mfma_f32_16x16x32_bf16 v[34:37], v[164:167], v[188:191], v[34:37]
	v_mfma_f32_16x16x32_bf16 v[26:29], v[172:175], v[188:191], v[26:29]
	v_mfma_f32_16x16x32_bf16 v[18:21], v[164:167], v[196:199], v[18:21]
	v_mfma_f32_16x16x32_bf16 v[10:13], v[172:175], v[196:199], v[10:13]
	v_mfma_f32_16x16x32_bf16 v[6:9], v[164:167], v[208:211], v[6:9]
	v_mfma_f32_16x16x32_bf16 v[2:5], v[172:175], v[208:211], v[2:5]
	v_mfma_f32_16x16x32_bf16 v[50:53], v[168:171], v[184:187], v[50:53]
	v_mfma_f32_16x16x32_bf16 v[42:45], v[176:179], v[184:187], v[42:45]
	v_mfma_f32_16x16x32_bf16 v[34:37], v[168:171], v[192:195], v[34:37]
	v_mfma_f32_16x16x32_bf16 v[26:29], v[176:179], v[192:195], v[26:29]
	v_mfma_f32_16x16x32_bf16 v[18:21], v[168:171], v[200:203], v[18:21]
	v_mfma_f32_16x16x32_bf16 v[10:13], v[176:179], v[200:203], v[10:13]
	v_mfma_f32_16x16x32_bf16 v[6:9], v[168:171], v[212:215], v[6:9]
	v_mfma_f32_16x16x32_bf16 v[2:5], v[176:179], v[212:215], v[2:5]
	s_setprio 0
	s_barrier
	s_add_i32 s83, 0, 0x18000
	v_add_u32_e32 v144, s83, v147
	s_add_i32 s84, 0, 0x1c000
	ds_read_b128 v[140:143], v144
	ds_read_b128 v[152:155], v144 offset:1024
	ds_read_b128 v[156:159], v144 offset:2048
	ds_read_b128 v[160:163], v144 offset:3072
	v_add_u32_e32 v144, s84, v147
	ds_read_b128 v[164:167], v144
	ds_read_b128 v[168:171], v144 offset:1024
	ds_read_b128 v[172:175], v144 offset:2048
	ds_read_b128 v[176:179], v144 offset:3072
	s_add_u32 s26, s62, 0x40000
	s_addc_u32 s27, s63, 0
	s_mov_b32 m0, s45
	ds_read_b128 v[180:183], v150 offset:32768
	ds_read_b128 v[184:187], v150 offset:33792
	ds_read_b128 v[188:191], v150 offset:34816
	ds_read_b128 v[192:195], v150 offset:35840
	ds_read_b128 v[196:199], v150 offset:36864
	ds_read_b128 v[200:203], v150 offset:37888
	ds_read_b128 v[208:211], v150 offset:38912
	ds_read_b128 v[212:215], v150 offset:39936
	global_load_lds_dwordx4 v134, s[26:27]
	s_mov_b32 m0, s64
	s_nop 0
	global_load_lds_dwordx4 v132, s[26:27]
	s_waitcnt vmcnt(8)
	s_waitcnt lgkmcnt(0)
	s_barrier
	s_setprio 1
	s_waitcnt lgkmcnt(0)
	v_mfma_f32_16x16x32_bf16 v[126:129], v[140:143], v[180:183], v[126:129]
	v_mfma_f32_16x16x32_bf16 v[122:125], v[156:159], v[180:183], v[122:125]
	v_mfma_f32_16x16x32_bf16 v[118:121], v[140:143], v[188:191], v[118:121]
	v_mfma_f32_16x16x32_bf16 v[110:113], v[156:159], v[188:191], v[110:113]
	v_mfma_f32_16x16x32_bf16 v[102:105], v[140:143], v[196:199], v[102:105]
	v_mfma_f32_16x16x32_bf16 v[94:97], v[156:159], v[196:199], v[94:97]
	v_mfma_f32_16x16x32_bf16 v[86:89], v[140:143], v[208:211], v[86:89]
	v_mfma_f32_16x16x32_bf16 v[78:81], v[156:159], v[208:211], v[78:81]
	v_mfma_f32_16x16x32_bf16 v[126:129], v[152:155], v[184:187], v[126:129]
	v_mfma_f32_16x16x32_bf16 v[122:125], v[160:163], v[184:187], v[122:125]
	v_mfma_f32_16x16x32_bf16 v[118:121], v[152:155], v[192:195], v[118:121]
	v_mfma_f32_16x16x32_bf16 v[110:113], v[160:163], v[192:195], v[110:113]
	v_mfma_f32_16x16x32_bf16 v[102:105], v[152:155], v[200:203], v[102:105]
	v_mfma_f32_16x16x32_bf16 v[94:97], v[160:163], v[200:203], v[94:97]
	v_mfma_f32_16x16x32_bf16 v[86:89], v[152:155], v[212:215], v[86:89]
	v_mfma_f32_16x16x32_bf16 v[78:81], v[160:163], v[212:215], v[78:81]
	s_setprio 0
	s_setprio 1
	v_mfma_f32_16x16x32_bf16 v[114:117], v[164:167], v[180:183], v[114:117]
	v_mfma_f32_16x16x32_bf16 v[106:109], v[172:175], v[180:183], v[106:109]
	v_mfma_f32_16x16x32_bf16 v[98:101], v[164:167], v[188:191], v[98:101]
	v_mfma_f32_16x16x32_bf16 v[90:93], v[172:175], v[188:191], v[90:93]
	v_mfma_f32_16x16x32_bf16 v[82:85], v[164:167], v[196:199], v[82:85]
	v_mfma_f32_16x16x32_bf16 v[74:77], v[172:175], v[196:199], v[74:77]
	v_mfma_f32_16x16x32_bf16 v[70:73], v[164:167], v[208:211], v[70:73]
	v_mfma_f32_16x16x32_bf16 v[66:69], v[172:175], v[208:211], v[66:69]
	v_mfma_f32_16x16x32_bf16 v[114:117], v[168:171], v[184:187], v[114:117]
	v_mfma_f32_16x16x32_bf16 v[106:109], v[176:179], v[184:187], v[106:109]
	v_mfma_f32_16x16x32_bf16 v[98:101], v[168:171], v[192:195], v[98:101]
	v_mfma_f32_16x16x32_bf16 v[90:93], v[176:179], v[192:195], v[90:93]
	v_mfma_f32_16x16x32_bf16 v[82:85], v[168:171], v[200:203], v[82:85]
	v_mfma_f32_16x16x32_bf16 v[74:77], v[176:179], v[200:203], v[74:77]
	v_mfma_f32_16x16x32_bf16 v[70:73], v[168:171], v[212:215], v[70:73]
	v_mfma_f32_16x16x32_bf16 v[66:69], v[176:179], v[212:215], v[66:69]
	s_setprio 0
	s_barrier
; #define PG8_STAGE(bufoff, gbase, voff) do { _Pragma("unroll") for (int _i = 0; _i < 2; ++_i) \
;         __builtin_amdgcn_global_load_lds((const unsigned*)((const char*)(gbase) + (voff)[_i]), (LAS unsigned*)(lds + (bufoff) + ldsw + _i * 8192), 16, 0, 0); } while (0)
; #define PG8_LDA(dst, b, h) do { _Pragma("unroll") for (int m = 0; m < 4; ++m) _Pragma("unroll") for (int k = 0; k < 2; ++k) dst[m][k] = *(const LAS bf16x8*)(lds + PG8_SA(b, h) + aoff + m * 2048 + k * 1024); } while (0)
; #define PG8_MMA(ai, bj, At, Bt) do { __builtin_amdgcn_s_setprio(1); _Pragma("unroll") for (int m = 0; m < 4; ++m) _Pragma("unroll") for (int n = 0; n < 2; ++n) _Pragma("unroll") for (int k = 0; k < 2; ++k) \
;         acc[ai][bj][m][n] = __builtin_amdgcn_mfma_f32_16x16x32_bf16(Bt[n][k], At[m][k], acc[ai][bj][m][n], 0, 0, 0); __builtin_amdgcn_s_setprio(0); } while (0)
; #define PG8_WAIT_V(n) asm volatile("s_waitcnt vmcnt(" #n ")" ::: "memory")
; #define PG8_WAIT_L(n) asm volatile("s_waitcnt lgkmcnt(" #n ")" ::: "memory")
; #define PG8_BAR __builtin_amdgcn_s_barrier()
; #define PG8_SCHED __builtin_amdgcn_sched_barrier(0)
; template <class Epi>
; DI void gemm_phase(LAS unsigned char* lds, const int tid, const Gemm g, const StaticOrder& S, const Epi& E) {
;     ...
;             PG8_LDA(At, 1, 1); PG8_STAGE(PG8_SB(1, 0), b3, voffB); PG8_STAGE(PG8_SB(1, 1), b3 + hstepB, voffB); PG8_STAGE(PG8_SA(1, 0), a3, voffA);
;             PG8_WAIT_V(8); PG8_WAIT_L(0); PG8_BAR; PG8_MMA(1, 0, At, B0); PG8_MMA(1, 1, At, B1); PG8_BAR; PG8_SCHED;
;         }
;         if (wr == 0) PG8_BAR;
	s_add_i32 s26, s83, s30
	v_lshl_add_u64 v[204:205], v[204:205], 0, s[54:55]
	s_mov_b32 m0, s26
	ds_read_b128 v[180:183], v150 offset:49152
	ds_read_b128 v[184:187], v150 offset:50176
	ds_read_b128 v[188:191], v150 offset:51200
	ds_read_b128 v[192:195], v150 offset:52224
	ds_read_b128 v[196:199], v150 offset:53248
	ds_read_b128 v[200:203], v150 offset:54272
	ds_read_b128 v[208:211], v150 offset:55296
	ds_read_b128 v[212:215], v150 offset:56320
	global_load_lds_dwordx4 v[204:205], off
	s_add_i32 m0, s26, 0x2000
	s_add_u32 s26, s60, 0x40080
	v_lshl_add_u64 v[204:205], v[216:217], 0, s[54:55]
	s_addc_u32 s27, s61, 0
	s_add_i32 s60, s84, s30
	global_load_lds_dwordx4 v[204:205], off
	s_mov_b32 m0, s60
	s_nop 0
	global_load_lds_dwordx4 v0, s[26:27]
	s_add_i32 m0, s60, 0x2000
	s_nop 0
	global_load_lds_dwordx4 v130, s[26:27]
	v_lshl_add_u64 v[204:205], v[218:219], 0, s[54:55]
	s_mov_b32 m0, s66
	s_nop 0
	global_load_lds_dwordx4 v[204:205], off
	v_lshl_add_u64 v[204:205], v[220:221], 0, s[54:55]
	s_mov_b32 m0, s67
	s_nop 0
	global_load_lds_dwordx4 v[204:205], off
	s_waitcnt vmcnt(8)
	s_waitcnt lgkmcnt(0)
	s_barrier
	s_setprio 1
	s_waitcnt lgkmcnt(0)
	v_mfma_f32_16x16x32_bf16 v[62:65], v[140:143], v[180:183], v[62:65]
	v_mfma_f32_16x16x32_bf16 v[58:61], v[156:159], v[180:183], v[58:61]
	v_mfma_f32_16x16x32_bf16 v[54:57], v[140:143], v[188:191], v[54:57]
	v_mfma_f32_16x16x32_bf16 v[46:49], v[156:159], v[188:191], v[46:49]
	v_mfma_f32_16x16x32_bf16 v[38:41], v[140:143], v[196:199], v[38:41]
	v_mfma_f32_16x16x32_bf16 v[30:33], v[156:159], v[196:199], v[30:33]
	v_mfma_f32_16x16x32_bf16 v[22:25], v[140:143], v[208:211], v[22:25]
	v_mfma_f32_16x16x32_bf16 v[14:17], v[156:159], v[208:211], v[14:17]
	v_mfma_f32_16x16x32_bf16 v[62:65], v[152:155], v[184:187], v[62:65]
	v_mfma_f32_16x16x32_bf16 v[58:61], v[160:163], v[184:187], v[58:61]
	v_mfma_f32_16x16x32_bf16 v[54:57], v[152:155], v[192:195], v[54:57]
	v_mfma_f32_16x16x32_bf16 v[46:49], v[160:163], v[192:195], v[46:49]
	v_mfma_f32_16x16x32_bf16 v[38:41], v[152:155], v[200:203], v[38:41]
	v_mfma_f32_16x16x32_bf16 v[30:33], v[160:163], v[200:203], v[30:33]
	v_mfma_f32_16x16x32_bf16 v[22:25], v[152:155], v[212:215], v[22:25]
	v_mfma_f32_16x16x32_bf16 v[14:17], v[160:163], v[212:215], v[14:17]
	s_setprio 0
	s_setprio 1
	v_mfma_f32_16x16x32_bf16 v[50:53], v[164:167], v[180:183], v[50:53]
	v_mfma_f32_16x16x32_bf16 v[42:45], v[172:175], v[180:183], v[42:45]
	v_mfma_f32_16x16x32_bf16 v[34:37], v[164:167], v[188:191], v[34:37]
	v_mfma_f32_16x16x32_bf16 v[26:29], v[172:175], v[188:191], v[26:29]
	v_mfma_f32_16x16x32_bf16 v[18:21], v[164:167], v[196:199], v[18:21]
	v_mfma_f32_16x16x32_bf16 v[10:13], v[172:175], v[196:199], v[10:13]
	v_mfma_f32_16x16x32_bf16 v[6:9], v[164:167], v[208:211], v[6:9]
	v_mfma_f32_16x16x32_bf16 v[2:5], v[172:175], v[208:211], v[2:5]
	v_mfma_f32_16x16x32_bf16 v[50:53], v[168:171], v[184:187], v[50:53]
	v_mfma_f32_16x16x32_bf16 v[42:45], v[176:179], v[184:187], v[42:45]
	v_mfma_f32_16x16x32_bf16 v[34:37], v[168:171], v[192:195], v[34:37]
	v_mfma_f32_16x16x32_bf16 v[26:29], v[176:179], v[192:195], v[26:29]
	v_mfma_f32_16x16x32_bf16 v[18:21], v[168:171], v[200:203], v[18:21]
	v_mfma_f32_16x16x32_bf16 v[10:13], v[176:179], v[200:203], v[10:13]
	v_mfma_f32_16x16x32_bf16 v[6:9], v[168:171], v[212:215], v[6:9]
	v_mfma_f32_16x16x32_bf16 v[2:5], v[176:179], v[212:215], v[2:5]
	s_setprio 0
	s_barrier
	s_add_i32 s82, s82, 2
	s_add_u32 s58, s58, 0x100
	s_addc_u32 s59, s59, 0
	s_add_u32 s80, s80, 0x100
	s_addc_u32 s81, s81, 0
	s_cmp_gt_u32 s82, 13
	s_cbranch_scc0 .LBB0_420
	s_and_b64 vcc, exec, s[10:11]
	s_cbranch_vccz .LBB0_423
	s_barrier

; #define PG8_STAGE(bufoff, gbase, voff) do { _Pragma("unroll") for (int _i = 0; _i < 2; ++_i) \
;         __builtin_amdgcn_global_load_lds((const unsigned*)((const char*)(gbase) + (voff)[_i]), (LAS unsigned*)(lds + (bufoff) + ldsw + _i * 8192), 16, 0, 0); } while (0)
; #define PG8_LDA(dst, b, h) do { _Pragma("unroll") for (int m = 0; m < 4; ++m) _Pragma("unroll") for (int k = 0; k < 2; ++k) dst[m][k] = *(const LAS bf16x8*)(lds + PG8_SA(b, h) + aoff + m * 2048 + k * 1024); } while (0)
; #define PG8_LDB(dst, b, h) do { _Pragma("unroll") for (int n = 0; n < 2; ++n) _Pragma("unroll") for (int k = 0; k < 2; ++k) dst[n][k] = *(const LAS bf16x8*)(lds + PG8_SB(b, h) + boff + n * 2048 + k * 1024); } while (0)
; #define PG8_MMA(ai, bj, At, Bt) do { __builtin_amdgcn_s_setprio(1); _Pragma("unroll") for (int m = 0; m < 4; ++m) _Pragma("unroll") for (int n = 0; n < 2; ++n) _Pragma("unroll") for (int k = 0; k < 2; ++k) \
;         acc[ai][bj][m][n] = __builtin_amdgcn_mfma_f32_16x16x32_bf16(Bt[n][k], At[m][k], acc[ai][bj][m][n], 0, 0, 0); __builtin_amdgcn_s_setprio(0); } while (0)
; #define PG8_WAIT_V(n) asm volatile("s_waitcnt vmcnt(" #n ")" ::: "memory")
; #define PG8_WAIT_L(n) asm volatile("s_waitcnt lgkmcnt(" #n ")" ::: "memory")
; #define PG8_BAR __builtin_amdgcn_s_barrier()
; #define PG8_SCHED __builtin_amdgcn_sched_barrier(0)
; template <class Epi>
; DI void gemm_phase(LAS unsigned char* lds, const int tid, const Gemm g, const StaticOrder& S, const Epi& E) {
;     ...
;         for (int t = 0; t < nt; t += 2) {
;             const bool last = (t == nt - 2);
;             const char* a1 = cA + (size_t)(t + 1) * kstep;
;             const char* a2 = last ? nA : cA + (size_t)(t + 2) * kstep; const char* b2 = last ? nB : cB + (size_t)(t + 2) * kstep;
;             const char* a3 = a2 + kstep; const char* b3 = b2 + kstep;
;             PG8_LDB(B0, 0, 0); PG8_LDB(B1, 0, 1); PG8_SCHED; PG8_LDA(At, 0, 0); PG8_STAGE(PG8_SA(1, 1), a1 + hstepA, voffA);
;             PG8_WAIT_V(8); PG8_WAIT_L(0); PG8_BAR; PG8_MMA(0, 0, At, B0); PG8_MMA(0, 1, At, B1); PG8_BAR; PG8_SCHED;
;             PG8_LDA(At, 0, 1); PG8_STAGE(PG8_SB(0, 0), b2, voffB); PG8_STAGE(PG8_SB(0, 1), b2 + hstepB, voffB); PG8_STAGE(PG8_SA(0, 0), a2, voffA);
;             PG8_WAIT_V(8); PG8_WAIT_L(0); PG8_BAR; PG8_MMA(1, 0, At, B0); PG8_MMA(1, 1, At, B1); PG8_BAR; PG8_SCHED;
.LBB0_453:
	s_add_i32 s82, s10, 2
	s_add_u32 s26, s8, s100
	s_addc_u32 s11, s9, 0
	s_add_i32 s27, 0, 0x10000
	s_cmp_eq_u32 s97, s10
	s_cselect_b32 s11, s37, s11
	s_cselect_b32 s10, s36, s26
	s_cselect_b32 vcc_hi, s81, s13
	s_cselect_b32 vcc_lo, s80, s12
	s_add_i32 s26, 0, 0x14000
	v_add_u32_e32 v142, s27, v251
	v_add_u32_e32 v158, s26, v251
	ds_read_b128 v[130:133], v142
	ds_read_b128 v[134:137], v142 offset:1024
	ds_read_b128 v[138:141], v142 offset:2048
	ds_read_b128 v[142:145], v142 offset:3072
	ds_read_b128 v[146:149], v158
	ds_read_b128 v[150:153], v158 offset:1024
	ds_read_b128 v[154:157], v158 offset:2048
	ds_read_b128 v[158:161], v158 offset:3072
	s_add_i32 m0, s31, 0xc000
	ds_read_b128 v[162:165], v243
	ds_read_b128 v[166:169], v243 offset:1024
	ds_read_b128 v[170:173], v243 offset:2048
	ds_read_b128 v[174:177], v243 offset:3072
	ds_read_b128 v[178:181], v243 offset:4096
	ds_read_b128 v[182:185], v243 offset:5120
	ds_read_b128 v[186:189], v243 offset:6144
	ds_read_b128 v[190:193], v243 offset:7168
	global_load_lds_dwordx4 v214, s[8:9]
	s_add_i32 m0, s31, 0xe000
	s_nop 0
	global_load_lds_dwordx4 v216, s[8:9]
	s_waitcnt vmcnt(8)
	s_waitcnt lgkmcnt(0)
	s_barrier
	s_setprio 1
	s_waitcnt lgkmcnt(0)
	v_mfma_f32_16x16x32_bf16 v[126:129], v[130:133], v[162:165], v[126:129]
	v_mfma_f32_16x16x32_bf16 v[122:125], v[138:141], v[162:165], v[122:125]
	v_mfma_f32_16x16x32_bf16 v[110:113], v[130:133], v[170:173], v[110:113]
	v_mfma_f32_16x16x32_bf16 v[106:109], v[138:141], v[170:173], v[106:109]
	v_mfma_f32_16x16x32_bf16 v[94:97], v[130:133], v[178:181], v[94:97]
	v_mfma_f32_16x16x32_bf16 v[90:93], v[138:141], v[178:181], v[90:93]
	v_mfma_f32_16x16x32_bf16 v[78:81], v[130:133], v[186:189], v[78:81]
	v_mfma_f32_16x16x32_bf16 v[74:77], v[138:141], v[186:189], v[74:77]
	v_mfma_f32_16x16x32_bf16 v[126:129], v[134:137], v[166:169], v[126:129]
	v_mfma_f32_16x16x32_bf16 v[122:125], v[142:145], v[166:169], v[122:125]
	v_mfma_f32_16x16x32_bf16 v[110:113], v[134:137], v[174:177], v[110:113]
	v_mfma_f32_16x16x32_bf16 v[106:109], v[142:145], v[174:177], v[106:109]
	v_mfma_f32_16x16x32_bf16 v[94:97], v[134:137], v[182:185], v[94:97]
	v_mfma_f32_16x16x32_bf16 v[90:93], v[142:145], v[182:185], v[90:93]
	v_mfma_f32_16x16x32_bf16 v[78:81], v[134:137], v[190:193], v[78:81]
	v_mfma_f32_16x16x32_bf16 v[74:77], v[142:145], v[190:193], v[74:77]
	s_setprio 0
	s_setprio 1
	v_mfma_f32_16x16x32_bf16 v[118:121], v[146:149], v[162:165], v[118:121]
	v_mfma_f32_16x16x32_bf16 v[114:117], v[154:157], v[162:165], v[114:117]
	v_mfma_f32_16x16x32_bf16 v[102:105], v[146:149], v[170:173], v[102:105]
	v_mfma_f32_16x16x32_bf16 v[98:101], v[154:157], v[170:173], v[98:101]
	v_mfma_f32_16x16x32_bf16 v[86:89], v[146:149], v[178:181], v[86:89]
	v_mfma_f32_16x16x32_bf16 v[82:85], v[154:157], v[178:181], v[82:85]
	v_mfma_f32_16x16x32_bf16 v[70:73], v[146:149], v[186:189], v[70:73]
	v_mfma_f32_16x16x32_bf16 v[66:69], v[154:157], v[186:189], v[66:69]
	v_mfma_f32_16x16x32_bf16 v[118:121], v[150:153], v[166:169], v[118:121]
	v_mfma_f32_16x16x32_bf16 v[114:117], v[158:161], v[166:169], v[114:117]
	v_mfma_f32_16x16x32_bf16 v[102:105], v[150:153], v[174:177], v[102:105]
	v_mfma_f32_16x16x32_bf16 v[98:101], v[158:161], v[174:177], v[98:101]
	v_mfma_f32_16x16x32_bf16 v[86:89], v[150:153], v[182:185], v[86:89]
	v_mfma_f32_16x16x32_bf16 v[82:85], v[158:161], v[182:185], v[82:85]
	v_mfma_f32_16x16x32_bf16 v[70:73], v[150:153], v[190:193], v[70:73]
	v_mfma_f32_16x16x32_bf16 v[66:69], v[158:161], v[190:193], v[66:69]
	s_setprio 0
	s_barrier
	s_add_i32 s27, s27, s30
	v_lshl_add_u64 v[194:195], vcc, 0, v[0:1]
	s_mov_b32 m0, s27
	ds_read_b128 v[162:165], v243 offset:16384
	ds_read_b128 v[166:169], v243 offset:17408
	ds_read_b128 v[170:173], v243 offset:18432
	ds_read_b128 v[174:177], v243 offset:19456
	ds_read_b128 v[178:181], v243 offset:20480
	ds_read_b128 v[182:185], v243 offset:21504
	ds_read_b128 v[186:189], v243 offset:22528
	ds_read_b128 v[190:193], v243 offset:23552
	global_load_lds_dwordx4 v[194:195], off
	s_add_i32 m0, s27, 0x2000
	v_lshl_add_u64 v[196:197], vcc, 0, v[208:209]
	s_add_u32 vcc_lo, vcc_lo, s14
	s_addc_u32 vcc_hi, vcc_hi, 0
	s_add_i32 s26, s26, s30
	global_load_lds_dwordx4 v[196:197], off
	v_lshl_add_u64 v[198:199], vcc, 0, v[0:1]
	s_mov_b32 m0, s26
	v_lshl_add_u64 v[200:201], vcc, 0, v[208:209]
	global_load_lds_dwordx4 v[198:199], off
	s_add_i32 m0, s26, 0x2000
	v_lshl_add_u64 v[202:203], s[10:11], 0, v[212:213]
	global_load_lds_dwordx4 v[200:201], off
	s_mov_b32 m0, s31
	v_lshl_add_u64 v[204:205], s[10:11], 0, v[210:211]
	global_load_lds_dwordx4 v212, s[10:11]
	s_mov_b32 m0, s38
	s_nop 0
	global_load_lds_dwordx4 v210, s[10:11]
	s_waitcnt vmcnt(8)
	s_waitcnt lgkmcnt(0)
	s_barrier
; #define PG8_STAGE(bufoff, gbase, voff) do { _Pragma("unroll") for (int _i = 0; _i < 2; ++_i) \
;         __builtin_amdgcn_global_load_lds((const unsigned*)((const char*)(gbase) + (voff)[_i]), (LAS unsigned*)(lds + (bufoff) + ldsw + _i * 8192), 16, 0, 0); } while (0)
; #define PG8_LDA(dst, b, h) do { _Pragma("unroll") for (int m = 0; m < 4; ++m) _Pragma("unroll") for (int k = 0; k < 2; ++k) dst[m][k] = *(const LAS bf16x8*)(lds + PG8_SA(b, h) + aoff + m * 2048 + k * 1024); } while (0)
; #define PG8_LDB(dst, b, h) do { _Pragma("unroll") for (int n = 0; n < 2; ++n) _Pragma("unroll") for (int k = 0; k < 2; ++k) dst[n][k] = *(const LAS bf16x8*)(lds + PG8_SB(b, h) + boff + n * 2048 + k * 1024); } while (0)
; #define PG8_MMA(ai, bj, At, Bt) do { __builtin_amdgcn_s_setprio(1); _Pragma("unroll") for (int m = 0; m < 4; ++m) _Pragma("unroll") for (int n = 0; n < 2; ++n) _Pragma("unroll") for (int k = 0; k < 2; ++k) \
;         acc[ai][bj][m][n] = __builtin_amdgcn_mfma_f32_16x16x32_bf16(Bt[n][k], At[m][k], acc[ai][bj][m][n], 0, 0, 0); __builtin_amdgcn_s_setprio(0); } while (0)
; #define PG8_WAIT_V(n) asm volatile("s_waitcnt vmcnt(" #n ")" ::: "memory")
; #define PG8_WAIT_L(n) asm volatile("s_waitcnt lgkmcnt(" #n ")" ::: "memory")
; #define PG8_BAR __builtin_amdgcn_s_barrier()
; #define PG8_SCHED __builtin_amdgcn_sched_barrier(0)
; template <class Epi>
; DI void gemm_phase(LAS unsigned char* lds, const int tid, const Gemm g, const StaticOrder& S, const Epi& E) {
;     ...
;             PG8_WAIT_V(8); PG8_WAIT_L(0); PG8_BAR; PG8_MMA(1, 0, At, B0); PG8_MMA(1, 1, At, B1); PG8_BAR; PG8_SCHED;
;             PG8_LDB(B0, 1, 0); PG8_LDB(B1, 1, 1); PG8_SCHED; PG8_LDA(At, 1, 0); PG8_STAGE(PG8_SA(0, 1), a2 + hstepA, voffA);
;             PG8_WAIT_V(8); PG8_WAIT_L(0); PG8_BAR; PG8_MMA(0, 0, At, B0); PG8_MMA(0, 1, At, B1); PG8_BAR; PG8_SCHED;
	s_setprio 1
	s_waitcnt lgkmcnt(0)
	v_mfma_f32_16x16x32_bf16 v[62:65], v[130:133], v[162:165], v[62:65]
	v_mfma_f32_16x16x32_bf16 v[58:61], v[138:141], v[162:165], v[58:61]
	v_mfma_f32_16x16x32_bf16 v[46:49], v[130:133], v[170:173], v[46:49]
	v_mfma_f32_16x16x32_bf16 v[42:45], v[138:141], v[170:173], v[42:45]
	v_mfma_f32_16x16x32_bf16 v[30:33], v[130:133], v[178:181], v[30:33]
	v_mfma_f32_16x16x32_bf16 v[26:29], v[138:141], v[178:181], v[26:29]
	v_mfma_f32_16x16x32_bf16 v[14:17], v[130:133], v[186:189], v[14:17]
	v_mfma_f32_16x16x32_bf16 v[10:13], v[138:141], v[186:189], v[10:13]
	v_mfma_f32_16x16x32_bf16 v[62:65], v[134:137], v[166:169], v[62:65]
	v_mfma_f32_16x16x32_bf16 v[58:61], v[142:145], v[166:169], v[58:61]
	v_mfma_f32_16x16x32_bf16 v[46:49], v[134:137], v[174:177], v[46:49]
	v_mfma_f32_16x16x32_bf16 v[42:45], v[142:145], v[174:177], v[42:45]
	v_mfma_f32_16x16x32_bf16 v[30:33], v[134:137], v[182:185], v[30:33]
	v_mfma_f32_16x16x32_bf16 v[26:29], v[142:145], v[182:185], v[26:29]
	v_mfma_f32_16x16x32_bf16 v[14:17], v[134:137], v[190:193], v[14:17]
	v_mfma_f32_16x16x32_bf16 v[10:13], v[142:145], v[190:193], v[10:13]
	s_setprio 0
	s_setprio 1
	v_mfma_f32_16x16x32_bf16 v[54:57], v[146:149], v[162:165], v[54:57]
	v_mfma_f32_16x16x32_bf16 v[50:53], v[154:157], v[162:165], v[50:53]
	v_mfma_f32_16x16x32_bf16 v[38:41], v[146:149], v[170:173], v[38:41]
	v_mfma_f32_16x16x32_bf16 v[34:37], v[154:157], v[170:173], v[34:37]
	v_mfma_f32_16x16x32_bf16 v[22:25], v[146:149], v[178:181], v[22:25]
	v_mfma_f32_16x16x32_bf16 v[18:21], v[154:157], v[178:181], v[18:21]
	v_mfma_f32_16x16x32_bf16 v[6:9], v[146:149], v[186:189], v[6:9]
	v_mfma_f32_16x16x32_bf16 v[2:5], v[154:157], v[186:189], v[2:5]
	v_mfma_f32_16x16x32_bf16 v[54:57], v[150:153], v[166:169], v[54:57]
	v_mfma_f32_16x16x32_bf16 v[50:53], v[158:161], v[166:169], v[50:53]
	v_mfma_f32_16x16x32_bf16 v[38:41], v[150:153], v[174:177], v[38:41]
	v_mfma_f32_16x16x32_bf16 v[34:37], v[158:161], v[174:177], v[34:37]
	v_mfma_f32_16x16x32_bf16 v[22:25], v[150:153], v[182:185], v[22:25]
	v_mfma_f32_16x16x32_bf16 v[18:21], v[158:161], v[182:185], v[18:21]
	v_mfma_f32_16x16x32_bf16 v[6:9], v[150:153], v[190:193], v[6:9]
	v_mfma_f32_16x16x32_bf16 v[2:5], v[158:161], v[190:193], v[2:5]
	s_setprio 0
	s_barrier
	s_add_i32 s26, 0, 0x18000
	s_add_i32 s27, 0, 0x1c000
	v_add_u32_e32 v142, s26, v251
	v_add_u32_e32 v158, s27, v251
	ds_read_b128 v[130:133], v142
	ds_read_b128 v[134:137], v142 offset:1024
	ds_read_b128 v[138:141], v142 offset:2048
	ds_read_b128 v[142:145], v142 offset:3072
	ds_read_b128 v[146:149], v158
	ds_read_b128 v[150:153], v158 offset:1024
	ds_read_b128 v[154:157], v158 offset:2048
	ds_read_b128 v[158:161], v158 offset:3072
	s_add_u32 s10, s10, s88
	s_addc_u32 s11, s11, 0
	s_mov_b32 m0, s45
	ds_read_b128 v[162:165], v243 offset:32768
	ds_read_b128 v[166:169], v243 offset:33792
	ds_read_b128 v[170:173], v243 offset:34816
	ds_read_b128 v[174:177], v243 offset:35840
	ds_read_b128 v[178:181], v243 offset:36864
	ds_read_b128 v[182:185], v243 offset:37888
	ds_read_b128 v[186:189], v243 offset:38912
	ds_read_b128 v[190:193], v243 offset:39936
	global_load_lds_dwordx4 v212, s[10:11]
	s_mov_b32 m0, s24
	s_nop 0
	global_load_lds_dwordx4 v210, s[10:11]
	s_waitcnt vmcnt(8)
	s_waitcnt lgkmcnt(0)
	s_barrier
	s_setprio 1
	s_waitcnt lgkmcnt(0)
	v_mfma_f32_16x16x32_bf16 v[126:129], v[130:133], v[162:165], v[126:129]
	v_mfma_f32_16x16x32_bf16 v[122:125], v[138:141], v[162:165], v[122:125]
	v_mfma_f32_16x16x32_bf16 v[110:113], v[130:133], v[170:173], v[110:113]
	v_mfma_f32_16x16x32_bf16 v[106:109], v[138:141], v[170:173], v[106:109]
	v_mfma_f32_16x16x32_bf16 v[94:97], v[130:133], v[178:181], v[94:97]
	v_mfma_f32_16x16x32_bf16 v[90:93], v[138:141], v[178:181], v[90:93]
	v_mfma_f32_16x16x32_bf16 v[78:81], v[130:133], v[186:189], v[78:81]
	v_mfma_f32_16x16x32_bf16 v[74:77], v[138:141], v[186:189], v[74:77]
	v_mfma_f32_16x16x32_bf16 v[126:129], v[134:137], v[166:169], v[126:129]
	v_mfma_f32_16x16x32_bf16 v[122:125], v[142:145], v[166:169], v[122:125]
	v_mfma_f32_16x16x32_bf16 v[110:113], v[134:137], v[174:177], v[110:113]
	v_mfma_f32_16x16x32_bf16 v[106:109], v[142:145], v[174:177], v[106:109]
	v_mfma_f32_16x16x32_bf16 v[94:97], v[134:137], v[182:185], v[94:97]
	v_mfma_f32_16x16x32_bf16 v[90:93], v[142:145], v[182:185], v[90:93]
	v_mfma_f32_16x16x32_bf16 v[78:81], v[134:137], v[190:193], v[78:81]
	v_mfma_f32_16x16x32_bf16 v[74:77], v[142:145], v[190:193], v[74:77]
	s_setprio 0
	s_setprio 1
	v_mfma_f32_16x16x32_bf16 v[118:121], v[146:149], v[162:165], v[118:121]
	v_mfma_f32_16x16x32_bf16 v[114:117], v[154:157], v[162:165], v[114:117]
	v_mfma_f32_16x16x32_bf16 v[102:105], v[146:149], v[170:173], v[102:105]
	v_mfma_f32_16x16x32_bf16 v[98:101], v[154:157], v[170:173], v[98:101]
	v_mfma_f32_16x16x32_bf16 v[86:89], v[146:149], v[178:181], v[86:89]
	v_mfma_f32_16x16x32_bf16 v[82:85], v[154:157], v[178:181], v[82:85]
	v_mfma_f32_16x16x32_bf16 v[70:73], v[146:149], v[186:189], v[70:73]
	v_mfma_f32_16x16x32_bf16 v[66:69], v[154:157], v[186:189], v[66:69]
	v_mfma_f32_16x16x32_bf16 v[118:121], v[150:153], v[166:169], v[118:121]
	v_mfma_f32_16x16x32_bf16 v[114:117], v[158:161], v[166:169], v[114:117]
	v_mfma_f32_16x16x32_bf16 v[102:105], v[150:153], v[174:177], v[102:105]
	v_mfma_f32_16x16x32_bf16 v[98:101], v[158:161], v[174:177], v[98:101]
	v_mfma_f32_16x16x32_bf16 v[86:89], v[150:153], v[182:185], v[86:89]
	v_mfma_f32_16x16x32_bf16 v[82:85], v[158:161], v[182:185], v[82:85]
	v_mfma_f32_16x16x32_bf16 v[70:73], v[150:153], v[190:193], v[70:73]
	v_mfma_f32_16x16x32_bf16 v[66:69], v[158:161], v[190:193], v[66:69]
	s_setprio 0
	s_barrier
; #define PG8_STAGE(bufoff, gbase, voff) do { _Pragma("unroll") for (int _i = 0; _i < 2; ++_i) \
;         __builtin_amdgcn_global_load_lds((const unsigned*)((const char*)(gbase) + (voff)[_i]), (LAS unsigned*)(lds + (bufoff) + ldsw + _i * 8192), 16, 0, 0); } while (0)
; #define PG8_LDA(dst, b, h) do { _Pragma("unroll") for (int m = 0; m < 4; ++m) _Pragma("unroll") for (int k = 0; k < 2; ++k) dst[m][k] = *(const LAS bf16x8*)(lds + PG8_SA(b, h) + aoff + m * 2048 + k * 1024); } while (0)
; #define PG8_MMA(ai, bj, At, Bt) do { __builtin_amdgcn_s_setprio(1); _Pragma("unroll") for (int m = 0; m < 4; ++m) _Pragma("unroll") for (int n = 0; n < 2; ++n) _Pragma("unroll") for (int k = 0; k < 2; ++k) \
;         acc[ai][bj][m][n] = __builtin_amdgcn_mfma_f32_16x16x32_bf16(Bt[n][k], At[m][k], acc[ai][bj][m][n], 0, 0, 0); __builtin_amdgcn_s_setprio(0); } while (0)
; #define PG8_WAIT_V(n) asm volatile("s_waitcnt vmcnt(" #n ")" ::: "memory")
; #define PG8_WAIT_L(n) asm volatile("s_waitcnt lgkmcnt(" #n ")" ::: "memory")
; #define PG8_BAR __builtin_amdgcn_s_barrier()
; #define PG8_SCHED __builtin_amdgcn_sched_barrier(0)
; template <class Epi>
; DI void gemm_phase(LAS unsigned char* lds, const int tid, const Gemm g, const StaticOrder& S, const Epi& E) {
;     ...
;             PG8_LDA(At, 1, 1); PG8_STAGE(PG8_SB(1, 0), b3, voffB); PG8_STAGE(PG8_SB(1, 1), b3 + hstepB, voffB); PG8_STAGE(PG8_SA(1, 0), a3, voffA);
;             PG8_WAIT_V(8); PG8_WAIT_L(0); PG8_BAR; PG8_MMA(1, 0, At, B0); PG8_MMA(1, 1, At, B1); PG8_BAR; PG8_SCHED;
;         }
;         if (wr == 0) PG8_BAR;
	s_add_i32 s10, s26, s30
	v_lshl_add_u64 v[194:195], v[194:195], 0, s[54:55]
	s_mov_b32 m0, s10
	ds_read_b128 v[162:165], v243 offset:49152
	ds_read_b128 v[166:169], v243 offset:50176
	ds_read_b128 v[170:173], v243 offset:51200
	ds_read_b128 v[174:177], v243 offset:52224
	ds_read_b128 v[178:181], v243 offset:53248
	ds_read_b128 v[182:185], v243 offset:54272
	ds_read_b128 v[186:189], v243 offset:55296
	ds_read_b128 v[190:193], v243 offset:56320
	global_load_lds_dwordx4 v[194:195], off
	v_lshl_add_u64 v[194:195], v[196:197], 0, s[54:55]
	s_add_i32 m0, s10, 0x2000
	s_add_i32 s10, s27, s30
	global_load_lds_dwordx4 v[194:195], off
	v_lshl_add_u64 v[194:195], v[198:199], 0, s[54:55]
	s_mov_b32 m0, s10
	s_nop 0
	global_load_lds_dwordx4 v[194:195], off
	v_lshl_add_u64 v[194:195], v[200:201], 0, s[54:55]
	s_add_i32 m0, s10, 0x2000
	s_nop 0
	global_load_lds_dwordx4 v[194:195], off
	v_lshl_add_u64 v[194:195], v[202:203], 0, s[100:101]
	s_mov_b32 m0, s25
	s_nop 0
	global_load_lds_dwordx4 v[194:195], off
	v_lshl_add_u64 v[194:195], v[204:205], 0, s[100:101]
	s_mov_b32 m0, s42
	s_nop 0
	global_load_lds_dwordx4 v[194:195], off
	s_waitcnt vmcnt(8)
	s_waitcnt lgkmcnt(0)
	s_barrier
	s_setprio 1
	s_waitcnt lgkmcnt(0)
	v_mfma_f32_16x16x32_bf16 v[62:65], v[130:133], v[162:165], v[62:65]
	v_mfma_f32_16x16x32_bf16 v[58:61], v[138:141], v[162:165], v[58:61]
	v_mfma_f32_16x16x32_bf16 v[46:49], v[130:133], v[170:173], v[46:49]
	v_mfma_f32_16x16x32_bf16 v[42:45], v[138:141], v[170:173], v[42:45]
	v_mfma_f32_16x16x32_bf16 v[30:33], v[130:133], v[178:181], v[30:33]
	v_mfma_f32_16x16x32_bf16 v[26:29], v[138:141], v[178:181], v[26:29]
	v_mfma_f32_16x16x32_bf16 v[14:17], v[130:133], v[186:189], v[14:17]
	v_mfma_f32_16x16x32_bf16 v[10:13], v[138:141], v[186:189], v[10:13]
	v_mfma_f32_16x16x32_bf16 v[62:65], v[134:137], v[166:169], v[62:65]
	v_mfma_f32_16x16x32_bf16 v[58:61], v[142:145], v[166:169], v[58:61]
	v_mfma_f32_16x16x32_bf16 v[46:49], v[134:137], v[174:177], v[46:49]
	v_mfma_f32_16x16x32_bf16 v[42:45], v[142:145], v[174:177], v[42:45]
	v_mfma_f32_16x16x32_bf16 v[30:33], v[134:137], v[182:185], v[30:33]
	v_mfma_f32_16x16x32_bf16 v[26:29], v[142:145], v[182:185], v[26:29]
	v_mfma_f32_16x16x32_bf16 v[14:17], v[134:137], v[190:193], v[14:17]
	v_mfma_f32_16x16x32_bf16 v[10:13], v[142:145], v[190:193], v[10:13]
	s_setprio 0
	s_setprio 1
	v_mfma_f32_16x16x32_bf16 v[54:57], v[146:149], v[162:165], v[54:57]
	v_mfma_f32_16x16x32_bf16 v[50:53], v[154:157], v[162:165], v[50:53]
	v_mfma_f32_16x16x32_bf16 v[38:41], v[146:149], v[170:173], v[38:41]
	v_mfma_f32_16x16x32_bf16 v[34:37], v[154:157], v[170:173], v[34:37]
	v_mfma_f32_16x16x32_bf16 v[22:25], v[146:149], v[178:181], v[22:25]
	v_mfma_f32_16x16x32_bf16 v[18:21], v[154:157], v[178:181], v[18:21]
	v_mfma_f32_16x16x32_bf16 v[6:9], v[146:149], v[186:189], v[6:9]
	v_mfma_f32_16x16x32_bf16 v[2:5], v[154:157], v[186:189], v[2:5]
	v_mfma_f32_16x16x32_bf16 v[54:57], v[150:153], v[166:169], v[54:57]
	v_mfma_f32_16x16x32_bf16 v[50:53], v[158:161], v[166:169], v[50:53]
	v_mfma_f32_16x16x32_bf16 v[38:41], v[150:153], v[174:177], v[38:41]
	v_mfma_f32_16x16x32_bf16 v[34:37], v[158:161], v[174:177], v[34:37]
	v_mfma_f32_16x16x32_bf16 v[22:25], v[150:153], v[182:185], v[22:25]
	v_mfma_f32_16x16x32_bf16 v[18:21], v[158:161], v[182:185], v[18:21]
	v_mfma_f32_16x16x32_bf16 v[6:9], v[150:153], v[190:193], v[6:9]
	v_mfma_f32_16x16x32_bf16 v[2:5], v[158:161], v[190:193], v[2:5]
	s_setprio 0
	s_barrier
	s_add_u32 s8, s8, s100
	s_addc_u32 s9, s9, 0
	s_add_u32 s8, s8, s100
	s_addc_u32 s9, s9, 0
	s_add_u32 s12, s12, 0x100
	s_addc_u32 s13, s13, 0
	s_cmp_ge_u32 s82, s96
	s_mov_b32 s10, s82
	s_cbranch_scc0 .LBB0_453
	s_and_b64 vcc, exec, s[56:57]
	s_cbranch_vccz .LBB0_456
	s_barrier
